# k13 + EpiResid epilogues (FFN down-proj, out-proj): next column group's residual loads issued before current group's stores, saddr+voffset addressing
# baseline (speedup 1.0000x reference)
.LBB0_409:
	v_mov_b32_e32 v137, v156
	s_mov_b32 s10, s67
	v_mov_b32_e32 v136, v157
	s_mov_b32 s11, s66
	s_lshl_b32 s12, s35, 8
	s_lshl_b32 s11, s11, 6
	s_add_i32 s11, s11, s12
	v_add_u32_e32 v136, s11, v136
	s_lshl_b32 s11, s40, 8
	s_lshl_b32 s10, s10, 5
	s_ashr_i32 s13, s35, 3
	s_add_i32 s10, s10, s11
	v_lshl_add_u32 v152, v137, 2, s10
	s_mul_hi_i32 s11, s13, 0x9000
	s_mul_i32 s13, s13, 0x9000
	s_add_u32 s10, s25, s13
	v_ashrrev_i32_e32 v153, 31, v152
	v_readlane_b32 s16, v254, 35
	v_ashrrev_i32_e32 v137, 31, v136
	s_addc_u32 s11, s26, s11
	v_lshlrev_b64 v[196:197], 2, v[152:153]
	v_readlane_b32 s17, v254, 36
	v_lshlrev_b64 v[138:139], 12, v[136:137]
	v_lshl_add_u64 v[154:155], s[10:11], 0, v[196:197]
	v_lshl_add_u64 v[192:193], s[16:17], 0, v[196:197]
	v_add_u32_e32 v222, v138, v196
	v_add_u32_e32 v223, 0x10000, v222
	v_add_u32_e32 v224, 0x20000, v222
	v_add_u32_e32 v234, 0x30000, v222
	v_add_u32_e32 v241, 0x80000, v222
	v_add_u32_e32 v243, 0x90000, v222
	v_add_u32_e32 v246, 0xa0000, v222
	v_add_u32_e32 v247, 0xb0000, v222
	global_load_dwordx4 v[160:163], v[154:155], off
	global_load_dwordx4 v[164:167], v222, s[16:17]
	global_load_dwordx4 v[168:171], v223, s[16:17]
	global_load_dwordx4 v[172:175], v224, s[16:17]
	global_load_dwordx4 v[176:179], v234, s[16:17]
	global_load_dwordx4 v[180:183], v241, s[16:17]
	global_load_dwordx4 v[184:187], v243, s[16:17]
	global_load_dwordx4 v[188:191], v246, s[16:17]
	global_load_dwordx4 v[192:195], v247, s[16:17]
	global_load_dwordx4 v[206:209], v[154:155], off offset:64
	global_load_dwordx4 v[136:139], v222, s[16:17] offset:64
	global_load_dwordx4 v[140:143], v223, s[16:17] offset:64
	global_load_dwordx4 v[144:147], v224, s[16:17] offset:64
	global_load_dwordx4 v[148:151], v234, s[16:17] offset:64
	global_load_dwordx4 v[214:217], v241, s[16:17] offset:64
	global_load_dwordx4 v[218:221], v243, s[16:17] offset:64
	global_load_dwordx4 v[226:229], v246, s[16:17] offset:64
	global_load_dwordx4 v[230:233], v247, s[16:17] offset:64
	s_mov_b64 s[10:11], 0x10000
	s_mov_b64 s[10:11], 0x20000
	s_mov_b64 s[10:11], 0x30000
	s_mov_b64 s[14:15], 0x80000
	s_mov_b64 s[10:11], 0x90000
	s_mov_b64 s[10:11], 0xa0000
	s_mov_b64 s[10:11], 0xb0000
	v_readlane_b32 s40, v253, 0
	v_readlane_b32 s52, v253, 12
	v_readlane_b32 s53, v253, 13
	v_readlane_b32 s54, v253, 14
	v_readlane_b32 s55, v253, 15
	s_mov_b64 s[12:13], s[52:53]
	s_mov_b64 s[14:15], s[54:55]
	s_mov_b64 s[10:11], -1
	s_and_b64 vcc, exec, s[6:7]
	v_readlane_b32 s41, v253, 1
	v_readlane_b32 s42, v253, 2
	v_readlane_b32 s43, v253, 3
	v_readlane_b32 s44, v253, 4
	v_readlane_b32 s45, v253, 5
	v_readlane_b32 s46, v253, 6
	v_readlane_b32 s47, v253, 7
	v_readlane_b32 s48, v253, 8
	v_readlane_b32 s49, v253, 9
	v_readlane_b32 s50, v253, 10
	v_readlane_b32 s51, v253, 11
	s_waitcnt vmcnt(9)
	v_pk_mul_f32 v[160:161], v[160:161], 0.5 op_sel_hi:[1,0]
	v_pk_mul_f32 v[162:163], v[162:163], 0.5 op_sel_hi:[1,0]
	v_pk_fma_f32 v[164:165], v[126:127], v[160:161], v[164:165]
	v_pk_fma_f32 v[166:167], v[128:129], v[162:163], v[166:167]
	global_store_dwordx4 v222, v[164:167], s[14:15]
	v_pk_fma_f32 v[168:169], v[122:123], v[160:161], v[168:169]
	v_pk_fma_f32 v[170:171], v[124:125], v[162:163], v[170:171]
	global_store_dwordx4 v223, v[168:171], s[14:15]
	v_pk_fma_f32 v[172:173], v[118:119], v[160:161], v[172:173]
	v_pk_fma_f32 v[174:175], v[120:121], v[162:163], v[174:175]
	global_store_dwordx4 v224, v[172:175], s[14:15]
	v_pk_fma_f32 v[176:177], v[114:115], v[160:161], v[176:177]
	v_pk_fma_f32 v[178:179], v[116:117], v[162:163], v[178:179]
	global_store_dwordx4 v234, v[176:179], s[14:15]
	v_pk_fma_f32 v[180:181], v[110:111], v[160:161], v[180:181]
	v_pk_fma_f32 v[182:183], v[112:113], v[162:163], v[182:183]
	global_store_dwordx4 v241, v[180:183], s[14:15]
	v_pk_fma_f32 v[184:185], v[106:107], v[160:161], v[184:185]
	v_pk_fma_f32 v[186:187], v[108:109], v[162:163], v[186:187]
	global_store_dwordx4 v243, v[184:187], s[14:15]
	v_pk_fma_f32 v[188:189], v[102:103], v[160:161], v[188:189]
	v_pk_fma_f32 v[190:191], v[104:105], v[162:163], v[190:191]
	global_store_dwordx4 v246, v[188:191], s[14:15]
	v_pk_fma_f32 v[192:193], v[98:99], v[160:161], v[192:193]
	v_pk_fma_f32 v[194:195], v[100:101], v[162:163], v[194:195]
	global_store_dwordx4 v247, v[192:195], s[14:15]
	global_load_dwordx4 v[160:163], v[154:155], off offset:512
	global_load_dwordx4 v[164:167], v222, s[16:17] offset:512
	global_load_dwordx4 v[168:171], v223, s[16:17] offset:512
	global_load_dwordx4 v[172:175], v224, s[16:17] offset:512
	global_load_dwordx4 v[176:179], v234, s[16:17] offset:512
	global_load_dwordx4 v[180:183], v241, s[16:17] offset:512
	global_load_dwordx4 v[184:187], v243, s[16:17] offset:512
	global_load_dwordx4 v[188:191], v246, s[16:17] offset:512
	global_load_dwordx4 v[192:195], v247, s[16:17] offset:512
	s_waitcnt vmcnt(17)
	v_pk_mul_f32 v[206:207], v[206:207], 0.5 op_sel_hi:[1,0]
	v_pk_mul_f32 v[208:209], v[208:209], 0.5 op_sel_hi:[1,0]
	v_pk_fma_f32 v[136:137], v[94:95], v[206:207], v[136:137]
	v_pk_fma_f32 v[138:139], v[96:97], v[208:209], v[138:139]
	global_store_dwordx4 v222, v[136:139], s[14:15] offset:64
	v_pk_fma_f32 v[140:141], v[90:91], v[206:207], v[140:141]
	v_pk_fma_f32 v[142:143], v[92:93], v[208:209], v[142:143]
	global_store_dwordx4 v223, v[140:143], s[14:15] offset:64
	v_pk_fma_f32 v[144:145], v[86:87], v[206:207], v[144:145]
	v_pk_fma_f32 v[146:147], v[88:89], v[208:209], v[146:147]
	global_store_dwordx4 v224, v[144:147], s[14:15] offset:64
	v_pk_fma_f32 v[148:149], v[82:83], v[206:207], v[148:149]
	v_pk_fma_f32 v[150:151], v[84:85], v[208:209], v[150:151]
	global_store_dwordx4 v234, v[148:151], s[14:15] offset:64
	v_pk_fma_f32 v[214:215], v[78:79], v[206:207], v[214:215]
	v_pk_fma_f32 v[216:217], v[80:81], v[208:209], v[216:217]
	global_store_dwordx4 v241, v[214:217], s[14:15] offset:64
	v_pk_fma_f32 v[218:219], v[74:75], v[206:207], v[218:219]
	v_pk_fma_f32 v[220:221], v[76:77], v[208:209], v[220:221]
	global_store_dwordx4 v243, v[218:221], s[14:15] offset:64
	v_pk_fma_f32 v[226:227], v[70:71], v[206:207], v[226:227]
	v_pk_fma_f32 v[228:229], v[72:73], v[208:209], v[228:229]
	global_store_dwordx4 v246, v[226:229], s[14:15] offset:64
	v_pk_fma_f32 v[230:231], v[66:67], v[206:207], v[230:231]
	v_pk_fma_f32 v[232:233], v[68:69], v[208:209], v[232:233]
	global_store_dwordx4 v247, v[230:233], s[14:15] offset:64
	global_load_dwordx4 v[206:209], v[154:155], off offset:576
	global_load_dwordx4 v[136:139], v222, s[16:17] offset:576
	global_load_dwordx4 v[140:143], v223, s[16:17] offset:576
	global_load_dwordx4 v[144:147], v224, s[16:17] offset:576
	global_load_dwordx4 v[148:151], v234, s[16:17] offset:576
	global_load_dwordx4 v[214:217], v241, s[16:17] offset:576
	global_load_dwordx4 v[218:221], v243, s[16:17] offset:576
	global_load_dwordx4 v[226:229], v246, s[16:17] offset:576
	global_load_dwordx4 v[230:233], v247, s[16:17] offset:576
	s_waitcnt vmcnt(17)
	v_pk_mul_f32 v[160:161], v[160:161], 0.5 op_sel_hi:[1,0]
	v_pk_mul_f32 v[162:163], v[162:163], 0.5 op_sel_hi:[1,0]
	v_pk_fma_f32 v[164:165], v[62:63], v[160:161], v[164:165]
	v_pk_fma_f32 v[166:167], v[64:65], v[162:163], v[166:167]
	global_store_dwordx4 v222, v[164:167], s[14:15] offset:512
	v_pk_fma_f32 v[168:169], v[58:59], v[160:161], v[168:169]
	v_pk_fma_f32 v[170:171], v[60:61], v[162:163], v[170:171]
	global_store_dwordx4 v223, v[168:171], s[14:15] offset:512
	v_pk_fma_f32 v[172:173], v[54:55], v[160:161], v[172:173]
	v_pk_fma_f32 v[174:175], v[56:57], v[162:163], v[174:175]
	global_store_dwordx4 v224, v[172:175], s[14:15] offset:512
	v_pk_fma_f32 v[176:177], v[50:51], v[160:161], v[176:177]
	v_pk_fma_f32 v[178:179], v[52:53], v[162:163], v[178:179]
	global_store_dwordx4 v234, v[176:179], s[14:15] offset:512
	v_pk_fma_f32 v[180:181], v[46:47], v[160:161], v[180:181]
	v_pk_fma_f32 v[182:183], v[48:49], v[162:163], v[182:183]
	global_store_dwordx4 v241, v[180:183], s[14:15] offset:512
	v_pk_fma_f32 v[184:185], v[42:43], v[160:161], v[184:185]
	v_pk_fma_f32 v[186:187], v[44:45], v[162:163], v[186:187]
	global_store_dwordx4 v243, v[184:187], s[14:15] offset:512
	v_pk_fma_f32 v[188:189], v[38:39], v[160:161], v[188:189]
	v_pk_fma_f32 v[190:191], v[40:41], v[162:163], v[190:191]
	global_store_dwordx4 v246, v[188:191], s[14:15] offset:512
	v_pk_fma_f32 v[192:193], v[34:35], v[160:161], v[192:193]
	v_pk_fma_f32 v[194:195], v[36:37], v[162:163], v[194:195]
	global_store_dwordx4 v247, v[192:195], s[14:15] offset:512
	s_waitcnt vmcnt(8)
	v_pk_mul_f32 v[206:207], v[206:207], 0.5 op_sel_hi:[1,0]
	v_pk_mul_f32 v[208:209], v[208:209], 0.5 op_sel_hi:[1,0]
	v_pk_fma_f32 v[136:137], v[30:31], v[206:207], v[136:137]
	v_pk_fma_f32 v[138:139], v[32:33], v[208:209], v[138:139]
	global_store_dwordx4 v222, v[136:139], s[14:15] offset:576
	v_pk_fma_f32 v[140:141], v[26:27], v[206:207], v[140:141]
	v_pk_fma_f32 v[142:143], v[28:29], v[208:209], v[142:143]
	global_store_dwordx4 v223, v[140:143], s[14:15] offset:576
	v_pk_fma_f32 v[144:145], v[22:23], v[206:207], v[144:145]
	v_pk_fma_f32 v[146:147], v[24:25], v[208:209], v[146:147]
	global_store_dwordx4 v224, v[144:147], s[14:15] offset:576
	v_pk_fma_f32 v[148:149], v[18:19], v[206:207], v[148:149]
	v_pk_fma_f32 v[150:151], v[20:21], v[208:209], v[150:151]
	global_store_dwordx4 v234, v[148:151], s[14:15] offset:576
	v_pk_fma_f32 v[214:215], v[14:15], v[206:207], v[214:215]
	v_pk_fma_f32 v[216:217], v[16:17], v[208:209], v[216:217]
	global_store_dwordx4 v241, v[214:217], s[14:15] offset:576
	v_pk_fma_f32 v[218:219], v[10:11], v[206:207], v[218:219]
	v_pk_fma_f32 v[220:221], v[12:13], v[208:209], v[220:221]
	global_store_dwordx4 v243, v[218:221], s[14:15] offset:576
	v_pk_fma_f32 v[226:227], v[6:7], v[206:207], v[226:227]
	v_pk_fma_f32 v[228:229], v[8:9], v[208:209], v[228:229]
	global_store_dwordx4 v246, v[226:229], s[14:15] offset:576
	v_pk_fma_f32 v[230:231], v[2:3], v[206:207], v[230:231]
	v_pk_fma_f32 v[232:233], v[4:5], v[208:209], v[232:233]
	global_store_dwordx4 v247, v[230:233], s[14:15] offset:576
	s_cbranch_vccnz .LBB0_394
	s_and_b64 vcc, exec, s[4:5]
	s_cbranch_vccnz .LBB0_393
	s_barrier
	s_branch .LBB0_393

.LBB0_1716:
	v_mov_b32_e32 v137, v156
	s_mov_b32 s1, s67
	v_mov_b32_e32 v136, v157
	s_mov_b32 s3, s66
	s_lshl_b32 s4, s12, 8
	s_lshl_b32 s3, s3, 6
	s_add_i32 s3, s3, s4
	v_add_u32_e32 v136, s3, v136
	s_lshl_b32 s3, s27, 8
	s_lshl_b32 s1, s1, 5
	s_add_i32 s1, s1, s3
	v_lshl_add_u32 v152, v137, 2, s1
	v_ashrrev_i32_e32 v137, 31, v136
	s_ashr_i32 s5, s12, 3
	v_lshlrev_b64 v[150:151], 12, v[136:137]
	s_mov_b64 s[14:15], 0x80000
	s_mul_hi_i32 s1, s5, 0x9000
	s_mul_i32 s5, s5, 0x9000
	v_lshl_add_u64 v[136:137], v[150:151], 0, s[14:15]
	v_readlane_b32 s3, v254, 32
	v_ashrrev_i32_e32 v153, 31, v152
	v_readlane_b32 s14, v254, 35
	s_add_u32 s4, s3, s5
	v_readlane_b32 s3, v254, 34
	v_lshlrev_b64 v[196:197], 2, v[152:153]
	v_readlane_b32 s15, v254, 36
	s_addc_u32 s5, s3, s1
	v_lshl_add_u64 v[154:155], s[4:5], 0, v[196:197]
	v_lshl_add_u64 v[192:193], s[14:15], 0, v[196:197]
	v_lshl_add_u64 v[138:139], v[192:193], 0, v[150:151]
	s_mov_b64 s[4:5], 0x10000
	v_add_u32_e32 v222, v150, v196
	v_add_u32_e32 v223, 0x10000, v222
	v_add_u32_e32 v224, 0x20000, v222
	v_add_u32_e32 v234, 0x30000, v222
	v_add_u32_e32 v241, 0x80000, v222
	v_add_u32_e32 v243, 0x90000, v222
	v_add_u32_e32 v246, 0xa0000, v222
	v_add_u32_e32 v247, 0xb0000, v222
	global_load_dwordx4 v[160:163], v[154:155], off
	global_load_dwordx4 v[164:167], v222, s[14:15]
	global_load_dwordx4 v[168:171], v223, s[14:15]
	global_load_dwordx4 v[172:175], v224, s[14:15]
	global_load_dwordx4 v[176:179], v234, s[14:15]
	global_load_dwordx4 v[180:183], v241, s[14:15]
	global_load_dwordx4 v[184:187], v243, s[14:15]
	global_load_dwordx4 v[188:191], v246, s[14:15]
	global_load_dwordx4 v[192:195], v247, s[14:15]
	global_load_dwordx4 v[206:209], v[154:155], off offset:64
	global_load_dwordx4 v[136:139], v222, s[14:15] offset:64
	global_load_dwordx4 v[140:143], v223, s[14:15] offset:64
	global_load_dwordx4 v[144:147], v224, s[14:15] offset:64
	global_load_dwordx4 v[148:151], v234, s[14:15] offset:64
	global_load_dwordx4 v[214:217], v241, s[14:15] offset:64
	global_load_dwordx4 v[218:221], v243, s[14:15] offset:64
	global_load_dwordx4 v[226:229], v246, s[14:15] offset:64
	global_load_dwordx4 v[230:233], v247, s[14:15] offset:64
	s_mov_b64 s[4:5], 0x20000
	s_mov_b64 s[4:5], 0x30000
	s_mov_b64 s[4:5], 0x90000
	s_mov_b64 s[4:5], 0xa0000
	s_mov_b64 s[4:5], 0xb0000
	v_readlane_b32 s40, v253, 0
	v_readlane_b32 s48, v253, 8
	v_readlane_b32 s49, v253, 9
	v_readlane_b32 s50, v253, 10
	v_readlane_b32 s51, v253, 11
	v_readlane_b32 s52, v253, 12
	v_readlane_b32 s53, v253, 13
	v_readlane_b32 s54, v253, 14
	v_readlane_b32 s55, v253, 15
	s_mov_b64 s[48:49], s[52:53]
	s_mov_b64 s[50:51], s[54:55]
	s_mov_b64 s[4:5], -1
	s_andn2_b64 vcc, exec, s[6:7]
	v_readlane_b32 s41, v253, 1
	v_readlane_b32 s42, v253, 2
	v_readlane_b32 s43, v253, 3
	v_readlane_b32 s44, v253, 4
	v_readlane_b32 s45, v253, 5
	v_readlane_b32 s46, v253, 6
	v_readlane_b32 s47, v253, 7
	s_waitcnt vmcnt(9)
	v_pk_fma_f32 v[164:165], v[126:127], v[160:161], v[164:165]
	v_pk_fma_f32 v[166:167], v[128:129], v[162:163], v[166:167]
	global_store_dwordx4 v222, v[164:167], s[50:51]
	v_pk_fma_f32 v[168:169], v[122:123], v[160:161], v[168:169]
	v_pk_fma_f32 v[170:171], v[124:125], v[162:163], v[170:171]
	global_store_dwordx4 v223, v[168:171], s[50:51]
	v_pk_fma_f32 v[172:173], v[118:119], v[160:161], v[172:173]
	v_pk_fma_f32 v[174:175], v[120:121], v[162:163], v[174:175]
	global_store_dwordx4 v224, v[172:175], s[50:51]
	v_pk_fma_f32 v[176:177], v[114:115], v[160:161], v[176:177]
	v_pk_fma_f32 v[178:179], v[116:117], v[162:163], v[178:179]
	global_store_dwordx4 v234, v[176:179], s[50:51]
	v_pk_fma_f32 v[180:181], v[110:111], v[160:161], v[180:181]
	v_pk_fma_f32 v[182:183], v[112:113], v[162:163], v[182:183]
	global_store_dwordx4 v241, v[180:183], s[50:51]
	v_pk_fma_f32 v[184:185], v[106:107], v[160:161], v[184:185]
	v_pk_fma_f32 v[186:187], v[108:109], v[162:163], v[186:187]
	global_store_dwordx4 v243, v[184:187], s[50:51]
	v_pk_fma_f32 v[188:189], v[102:103], v[160:161], v[188:189]
	v_pk_fma_f32 v[190:191], v[104:105], v[162:163], v[190:191]
	global_store_dwordx4 v246, v[188:191], s[50:51]
	v_pk_fma_f32 v[192:193], v[98:99], v[160:161], v[192:193]
	v_pk_fma_f32 v[194:195], v[100:101], v[162:163], v[194:195]
	global_store_dwordx4 v247, v[192:195], s[50:51]
	global_load_dwordx4 v[160:163], v[154:155], off offset:512
	global_load_dwordx4 v[164:167], v222, s[14:15] offset:512
	global_load_dwordx4 v[168:171], v223, s[14:15] offset:512
	global_load_dwordx4 v[172:175], v224, s[14:15] offset:512
	global_load_dwordx4 v[176:179], v234, s[14:15] offset:512
	global_load_dwordx4 v[180:183], v241, s[14:15] offset:512
	global_load_dwordx4 v[184:187], v243, s[14:15] offset:512
	global_load_dwordx4 v[188:191], v246, s[14:15] offset:512
	global_load_dwordx4 v[192:195], v247, s[14:15] offset:512
	s_waitcnt vmcnt(17)
	v_pk_fma_f32 v[136:137], v[94:95], v[206:207], v[136:137]
	v_pk_fma_f32 v[138:139], v[96:97], v[208:209], v[138:139]
	global_store_dwordx4 v222, v[136:139], s[50:51] offset:64
	v_pk_fma_f32 v[140:141], v[90:91], v[206:207], v[140:141]
	v_pk_fma_f32 v[142:143], v[92:93], v[208:209], v[142:143]
	global_store_dwordx4 v223, v[140:143], s[50:51] offset:64
	v_pk_fma_f32 v[144:145], v[86:87], v[206:207], v[144:145]
	v_pk_fma_f32 v[146:147], v[88:89], v[208:209], v[146:147]
	global_store_dwordx4 v224, v[144:147], s[50:51] offset:64
	v_pk_fma_f32 v[148:149], v[82:83], v[206:207], v[148:149]
	v_pk_fma_f32 v[150:151], v[84:85], v[208:209], v[150:151]
	global_store_dwordx4 v234, v[148:151], s[50:51] offset:64
	v_pk_fma_f32 v[214:215], v[78:79], v[206:207], v[214:215]
	v_pk_fma_f32 v[216:217], v[80:81], v[208:209], v[216:217]
	global_store_dwordx4 v241, v[214:217], s[50:51] offset:64
	v_pk_fma_f32 v[218:219], v[74:75], v[206:207], v[218:219]
	v_pk_fma_f32 v[220:221], v[76:77], v[208:209], v[220:221]
	global_store_dwordx4 v243, v[218:221], s[50:51] offset:64
	v_pk_fma_f32 v[226:227], v[70:71], v[206:207], v[226:227]
	v_pk_fma_f32 v[228:229], v[72:73], v[208:209], v[228:229]
	global_store_dwordx4 v246, v[226:229], s[50:51] offset:64
	v_pk_fma_f32 v[230:231], v[66:67], v[206:207], v[230:231]
	v_pk_fma_f32 v[232:233], v[68:69], v[208:209], v[232:233]
	global_store_dwordx4 v247, v[230:233], s[50:51] offset:64
	global_load_dwordx4 v[206:209], v[154:155], off offset:576
	global_load_dwordx4 v[136:139], v222, s[14:15] offset:576
	global_load_dwordx4 v[140:143], v223, s[14:15] offset:576
	global_load_dwordx4 v[144:147], v224, s[14:15] offset:576
	global_load_dwordx4 v[148:151], v234, s[14:15] offset:576
	global_load_dwordx4 v[214:217], v241, s[14:15] offset:576
	global_load_dwordx4 v[218:221], v243, s[14:15] offset:576
	global_load_dwordx4 v[226:229], v246, s[14:15] offset:576
	global_load_dwordx4 v[230:233], v247, s[14:15] offset:576
	s_waitcnt vmcnt(17)
	v_pk_fma_f32 v[164:165], v[62:63], v[160:161], v[164:165]
	v_pk_fma_f32 v[166:167], v[64:65], v[162:163], v[166:167]
	global_store_dwordx4 v222, v[164:167], s[50:51] offset:512
	v_pk_fma_f32 v[168:169], v[58:59], v[160:161], v[168:169]
	v_pk_fma_f32 v[170:171], v[60:61], v[162:163], v[170:171]
	global_store_dwordx4 v223, v[168:171], s[50:51] offset:512
	v_pk_fma_f32 v[172:173], v[54:55], v[160:161], v[172:173]
	v_pk_fma_f32 v[174:175], v[56:57], v[162:163], v[174:175]
	global_store_dwordx4 v224, v[172:175], s[50:51] offset:512
	v_pk_fma_f32 v[176:177], v[50:51], v[160:161], v[176:177]
	v_pk_fma_f32 v[178:179], v[52:53], v[162:163], v[178:179]
	global_store_dwordx4 v234, v[176:179], s[50:51] offset:512
	v_pk_fma_f32 v[180:181], v[46:47], v[160:161], v[180:181]
	v_pk_fma_f32 v[182:183], v[48:49], v[162:163], v[182:183]
	global_store_dwordx4 v241, v[180:183], s[50:51] offset:512
	v_pk_fma_f32 v[184:185], v[42:43], v[160:161], v[184:185]
	v_pk_fma_f32 v[186:187], v[44:45], v[162:163], v[186:187]
	global_store_dwordx4 v243, v[184:187], s[50:51] offset:512
	v_pk_fma_f32 v[188:189], v[38:39], v[160:161], v[188:189]
	v_pk_fma_f32 v[190:191], v[40:41], v[162:163], v[190:191]
	global_store_dwordx4 v246, v[188:191], s[50:51] offset:512
	v_pk_fma_f32 v[192:193], v[34:35], v[160:161], v[192:193]
	v_pk_fma_f32 v[194:195], v[36:37], v[162:163], v[194:195]
	global_store_dwordx4 v247, v[192:195], s[50:51] offset:512
	s_waitcnt vmcnt(8)
	v_pk_fma_f32 v[136:137], v[30:31], v[206:207], v[136:137]
	v_pk_fma_f32 v[138:139], v[32:33], v[208:209], v[138:139]
	global_store_dwordx4 v222, v[136:139], s[50:51] offset:576
	v_pk_fma_f32 v[140:141], v[26:27], v[206:207], v[140:141]
	v_pk_fma_f32 v[142:143], v[28:29], v[208:209], v[142:143]
	global_store_dwordx4 v223, v[140:143], s[50:51] offset:576
	v_pk_fma_f32 v[144:145], v[22:23], v[206:207], v[144:145]
	v_pk_fma_f32 v[146:147], v[24:25], v[208:209], v[146:147]
	global_store_dwordx4 v224, v[144:147], s[50:51] offset:576
	v_pk_fma_f32 v[148:149], v[18:19], v[206:207], v[148:149]
	v_pk_fma_f32 v[150:151], v[20:21], v[208:209], v[150:151]
	global_store_dwordx4 v234, v[148:151], s[50:51] offset:576
	v_pk_fma_f32 v[214:215], v[14:15], v[206:207], v[214:215]
	v_pk_fma_f32 v[216:217], v[16:17], v[208:209], v[216:217]
	global_store_dwordx4 v241, v[214:217], s[50:51] offset:576
	v_pk_fma_f32 v[218:219], v[10:11], v[206:207], v[218:219]
	v_pk_fma_f32 v[220:221], v[12:13], v[208:209], v[220:221]
	global_store_dwordx4 v243, v[218:221], s[50:51] offset:576
	v_pk_fma_f32 v[226:227], v[6:7], v[206:207], v[226:227]
	v_pk_fma_f32 v[228:229], v[8:9], v[208:209], v[228:229]
	global_store_dwordx4 v246, v[226:229], s[50:51] offset:576
	v_pk_fma_f32 v[230:231], v[2:3], v[206:207], v[230:231]
	v_pk_fma_f32 v[232:233], v[4:5], v[208:209], v[232:233]
	global_store_dwordx4 v247, v[230:233], s[50:51] offset:576
	s_cbranch_vccnz .LBB0_1705
	v_readlane_b32 s4, v254, 45
	v_readlane_b32 s5, v254, 46
	s_and_b64 vcc, exec, s[4:5]
	s_cbranch_vccnz .LBB0_1704
	s_barrier
	s_branch .LBB0_1704
